# dilated attention restructured to a single pass: raw f32 outputs to free scratch + lse/sum in LDS, then a per-window scaling loop (same formula) writes bf16; removes the duplicate QK^T+softmax pass
# speedup vs baseline: 1.0218x; 1.0215x over previous
.LBB0_1980:
	s_ashr_i32 s83, s74, 8
	s_lshl_b32 s83, s83, 14
	s_add_i32 s83, s83, s80
	v_mov_b32_e32 v228, s48
	v_mov_b32_e32 v229, s49
	v_mov_b32_e32 v230, 0xee000000
	v_mov_b32_e32 v231, -1
	v_lshl_add_u64 v[228:229], v[228:229], 0, v[230:231]
	v_mov_b32_e32 v119, 0xffff0000
	v_mov_b32_e32 v100, v176
	s_mov_b32 s86, 0
.Ldil_cv:
	v_lshrrev_b32_e32 v101, 3, v100
	v_and_b32_e32 v102, 7, v100
	v_lshlrev_b32_e32 v102, 3, v102
	v_lshrrev_b32_e32 v103, 8, v101
	v_and_b32_e32 v104, 0xff, v101
	v_add_u32_e32 v105, s83, v104
	v_lshlrev_b32_e32 v103, 2, v103
	v_add_u32_e32 v103, s75, v103
	v_lshlrev_b32_e32 v103, 6, v103
	v_lshl_add_u32 v105, v105, 10, v103
	v_add_u32_e32 v105, v105, v102
	v_lshlrev_b32_e32 v106, 2, v105
	v_mov_b32_e32 v107, 0
	v_lshl_add_u64 v[106:107], v[106:107], 0, v[228:229]
	v_lshlrev_b32_e32 v108, 1, v105
	v_mov_b32_e32 v109, 0
	v_lshl_add_u64 v[108:109], v[108:109], 0, s[48:49]
	global_load_dwordx4 v[110:113], v[106:107], off
	global_load_dwordx4 v[114:117], v[106:107], off offset:16
	s_waitcnt vmcnt(0)
	v_lshlrev_b32_e32 v124, 2, v104
	v_lshlrev_b32_e32 v128, 2, v101
	ds_read_b32 v125, v124 offset:1584
	ds_read_b32 v126, v124 offset:2608
	ds_read_b32 v127, v124 offset:3632
	ds_read_b32 v129, v128 offset:1584
	ds_read_b32 v130, v128 offset:50736
	s_waitcnt lgkmcnt(0)
	v_max3_f32 v131, v125, v126, v127
	v_sub_f32_e32 v125, v125, v131
	v_sub_f32_e32 v126, v126, v131
	v_mul_f32_e32 v125, 0x3fb8aa3b, v125
	v_mul_f32_e32 v126, 0x3fb8aa3b, v126
	v_exp_f32_e32 v125, v125
	v_exp_f32_e32 v126, v126
	v_sub_f32_e32 v127, v127, v131
	v_mul_f32_e32 v127, 0x3fb8aa3b, v127
	v_exp_f32_e32 v127, v127
	v_add_f32_e32 v125, v125, v126
	v_sub_f32_e32 v126, v129, v131
	v_mul_f32_e32 v126, 0x3fb8aa3b, v126
	v_exp_f32_e32 v126, v126
	v_add_f32_e32 v127, v127, v125
	v_mul_f32_e32 v127, v130, v127
	v_div_scale_f32 v130, s[88:89], v127, v127, v126
	v_rcp_f32_e32 v125, v130
	s_nop 0
	v_fma_f32 v131, -v130, v125, 1.0
	v_fmac_f32_e32 v125, v131, v125
	v_div_scale_f32 v131, vcc, v126, v127, v126
	v_mul_f32_e32 v132, v131, v125
	v_fma_f32 v133, -v130, v132, v131
	v_fmac_f32_e32 v132, v133, v125
	v_fma_f32 v130, -v130, v132, v131
	v_div_fmas_f32 v130, v130, v125, v132
	v_div_fixup_f32 v124, v130, v127, v126
	v_mul_f32_e32 v110, v124, v110
	v_mul_f32_e32 v111, v124, v111
	v_mul_f32_e32 v112, v124, v112
	v_mul_f32_e32 v113, v124, v113
	v_mul_f32_e32 v114, v124, v114
	v_mul_f32_e32 v115, v124, v115
	v_mul_f32_e32 v116, v124, v116
	v_mul_f32_e32 v117, v124, v117
	v_bfe_u32 v118, v110, 16, 1
	v_add3_u32 v110, v110, v118, s70
	v_bfe_u32 v118, v111, 16, 1
	v_add3_u32 v111, v111, v118, s70
	v_lshrrev_b32_e32 v110, 16, v110
	v_and_or_b32 v120, v111, v119, v110
	v_bfe_u32 v118, v112, 16, 1
	v_add3_u32 v112, v112, v118, s70
	v_bfe_u32 v118, v113, 16, 1
	v_add3_u32 v113, v113, v118, s70
	v_lshrrev_b32_e32 v112, 16, v112
	v_and_or_b32 v121, v113, v119, v112
	v_bfe_u32 v118, v114, 16, 1
	v_add3_u32 v114, v114, v118, s70
	v_bfe_u32 v118, v115, 16, 1
	v_add3_u32 v115, v115, v118, s70
	v_lshrrev_b32_e32 v114, 16, v114
	v_and_or_b32 v122, v115, v119, v114
	v_bfe_u32 v118, v116, 16, 1
	v_add3_u32 v116, v116, v118, s70
	v_bfe_u32 v118, v117, 16, 1
	v_add3_u32 v117, v117, v118, s70
	v_lshrrev_b32_e32 v116, 16, v116
	v_and_or_b32 v123, v117, v119, v116
	global_store_dwordx4 v[108:109], v[120:123], off
	v_add_u32_e32 v100, 0x200, v100
	s_add_i32 s86, s86, 1
	s_cmp_lt_u32 s86, 12
	s_cbranch_scc1 .Ldil_cv
	s_load_dword s4, s[50:51], 0x0
	s_waitcnt lgkmcnt(0)
	s_add_i32 s74, s4, s74
	s_cmpk_gt_i32 s74, 0x1ff
	s_cbranch_scc1 .LBB0_2085

.LBB0_1983:
	s_or_b64 exec, exec, s[4:5]
	s_lshl_b32 s4, s74, 6
	s_ashr_i32 s26, s74, 8
	s_and_b32 s80, s4, 0x3f00
	s_lshr_b32 s28, s80, 4
	s_ashr_i32 s27, s26, 31
	s_lshr_b32 s81, s80, 2
	s_lshl_b64 s[4:5], s[26:27], 14
	s_mul_i32 s82, s26, 12
	s_mov_b64 s[26:27], 0
	v_mov_b32_e32 v70, s28
	s_waitcnt lgkmcnt(0)
	s_barrier
	s_branch .LBB0_1985

.Ldil_skipv:
	s_mov_b64 s[52:53], 0
	v_lshl_add_u32 v80, v60, 2, v36
	v_mov_b32_e32 v78, 0xf149f2ca
	s_and_saveexec_b64 s[28:29], s[30:31]
	s_cbranch_execz .LBB0_1989
	ds_read_b32 v78, v80 offset:576
	s_waitcnt lgkmcnt(0)
	v_add_f32_e32 v78, v32, v78

.LBB0_2005:
	s_or_b64 exec, exec, s[44:45]
	v_max_f32_e32 v4, v78, v78
	v_max_f32_e32 v4, 0xf149f2ca, v4
	v_max3_f32 v4, v4, v77, v32
	v_max3_f32 v4, v4, v28, v87
	v_max3_f32 v4, v4, v79, v8
	v_max3_f32 v4, v4, v0, v49
	v_mov_b32_e32 v12, v37
	v_cmp_lt_f32_e32 vcc, s69, v78
	s_nop 0
	v_mov_b32_dpp v12, v4 row_ror:8 row_mask:0xf bank_mask:0xf
	v_max_f32_e32 v12, v12, v12
	v_max_f32_e32 v4, v4, v12
	v_mov_b32_e32 v12, v37
	s_nop 1
	v_mov_b32_dpp v12, v4 row_ror:4 row_mask:0xf bank_mask:0xf
	v_max_f32_e32 v12, v12, v12
	v_max_f32_e32 v4, v4, v12
	v_mov_b32_e32 v12, v37
	s_nop 1
	v_mov_b32_dpp v12, v4 row_ror:2 row_mask:0xf bank_mask:0xf
	v_max_f32_e32 v12, v12, v12
	v_max_f32_e32 v4, v4, v12
	v_mov_b32_e32 v12, v37
	s_nop 1
	v_mov_b32_dpp v12, v4 row_ror:1 row_mask:0xf bank_mask:0xf
	v_max_f32_e32 v12, v12, v12
	v_max_f32_e32 v4, v4, v12
	v_sub_f32_e32 v12, v78, v4
	v_mul_f32_e32 v12, 0x3fb8aa3b, v12
	v_sub_f32_e32 v16, v77, v4
	v_exp_f32_e32 v12, v12
	v_mul_f32_e32 v16, 0x3fb8aa3b, v16
	v_sub_f32_e32 v24, v32, v4
	v_exp_f32_e32 v16, v16
	v_mul_f32_e32 v24, 0x3fb8aa3b, v24
	v_exp_f32_e32 v24, v24
	v_cndmask_b32_e32 v12, 0, v12, vcc
	v_cmp_lt_f32_e32 vcc, s69, v77
	v_add_f32_e32 v20, 0, v12
	v_sub_f32_e32 v78, v8, v4
	v_cndmask_b32_e32 v16, 0, v16, vcc
	v_cmp_lt_f32_e32 vcc, s69, v32
	v_add_f32_e32 v77, v16, v20
	v_mul_f32_e32 v78, 0x3fb8aa3b, v78
	v_cndmask_b32_e32 v20, 0, v24, vcc
	v_sub_f32_e32 v24, v28, v4
	v_add_f32_e32 v32, v20, v77
	v_mul_f32_e32 v24, 0x3fb8aa3b, v24
	v_sub_f32_e32 v77, v87, v4
	v_exp_f32_e32 v24, v24
	v_mul_f32_e32 v77, 0x3fb8aa3b, v77
	v_exp_f32_e32 v77, v77
	v_cmp_lt_f32_e32 vcc, s69, v28
	v_exp_f32_e32 v78, v78
	s_nop 0
	v_cndmask_b32_e32 v24, 0, v24, vcc
	v_cmp_lt_f32_e32 vcc, s69, v87
	v_add_f32_e32 v32, v24, v32
	v_subrev_u32_e32 v87, s80, v76
	v_cndmask_b32_e32 v28, 0, v77, vcc
	v_add_f32_e32 v77, v28, v32
	v_sub_f32_e32 v32, v79, v4
	v_mul_f32_e32 v32, 0x3fb8aa3b, v32
	v_exp_f32_e32 v32, v32
	v_cmp_lt_f32_e32 vcc, s69, v79
	s_nop 1
	v_cndmask_b32_e32 v32, 0, v32, vcc
	v_cmp_lt_f32_e32 vcc, s69, v8
	v_add_f32_e32 v79, v32, v77
	s_nop 0
	v_cndmask_b32_e32 v77, 0, v78, vcc
	v_sub_f32_e32 v78, v0, v4
	v_add_f32_e32 v8, v77, v79
	v_mul_f32_e32 v78, 0x3fb8aa3b, v78
	v_sub_f32_e32 v79, v49, v4
	v_exp_f32_e32 v78, v78
	v_mul_f32_e32 v79, 0x3fb8aa3b, v79
	v_exp_f32_e32 v79, v79
	v_cmp_lt_f32_e32 vcc, s69, v0
	s_nop 1
	v_cndmask_b32_e32 v78, 0, v78, vcc
	v_cmp_lt_f32_e32 vcc, s69, v49
	v_add_f32_e32 v0, v78, v8
	s_nop 0
	v_cndmask_b32_e32 v79, 0, v79, vcc
	v_add_f32_e32 v0, v79, v0
	s_nop 1
	v_add_f32_dpp v0, v0, v0 row_ror:8 row_mask:0xf bank_mask:0xf bound_ctrl:1
	s_nop 1
	v_add_f32_dpp v0, v0, v0 row_ror:4 row_mask:0xf bank_mask:0xf bound_ctrl:1
	s_nop 1
	v_add_f32_dpp v0, v0, v0 row_ror:2 row_mask:0xf bank_mask:0xf bound_ctrl:1
	s_nop 1
	v_add_f32_dpp v49, v0, v0 row_ror:1 row_mask:0xf bank_mask:0xf bound_ctrl:1
	v_mov_b32_e32 v240, v49
	v_cmp_gt_f32_e32 vcc, s56, v49
	s_nop 1
	v_cndmask_b32_e64 v0, 0, 32, vcc
	v_ldexp_f32 v0, v49, v0
	v_log_f32_e32 v8, v0
	v_or_b32_e32 v0, v75, v52
	v_mul_f32_e32 v89, 0x3f317217, v8
	v_fma_f32 v89, v8, s57, -v89
	v_fmac_f32_e32 v89, 0x3377d1cf, v8
	v_fmac_f32_e32 v89, 0x3f317217, v8
	v_cmp_lt_f32_e64 s[44:45], |v8|, s58
	s_nop 1
	v_cndmask_b32_e64 v8, v8, v89, s[44:45]
	v_cndmask_b32_e32 v89, 0, v55, vcc
	v_sub_f32_e32 v8, v8, v89
	v_add_f32_e32 v4, v4, v8
	v_lshl_add_u32 v89, v0, v73, v87
	s_mov_b64 s[44:45], -1
	s_and_b64 vcc, exec, s[52:53]
	s_cbranch_vccz .LBB0_2007
	v_lshlrev_b32_e32 v8, 2, v89
	v_add_u32_e32 v90, 48, v8
	ds_read_b32 v8, v8 offset:3632
	ds_read2st64_b32 v[90:91], v90 offset0:6 offset1:10
	s_waitcnt lgkmcnt(0)
	v_max3_f32 v92, v90, v91, v8
	v_sub_f32_e32 v90, v90, v92
	v_sub_f32_e32 v91, v91, v92
	v_mul_f32_e32 v90, 0x3fb8aa3b, v90
	v_mul_f32_e32 v91, 0x3fb8aa3b, v91
	v_exp_f32_e32 v90, v90
	v_exp_f32_e32 v91, v91
	v_sub_f32_e32 v8, v8, v92
	v_mul_f32_e32 v8, 0x3fb8aa3b, v8
	v_exp_f32_e32 v8, v8
	v_add_f32_e32 v90, v90, v91
	v_sub_f32_e32 v91, v4, v92
	v_mul_f32_e32 v91, 0x3fb8aa3b, v91
	v_exp_f32_e32 v91, v91
	v_add_f32_e32 v8, v8, v90
	v_mul_f32_e32 v8, v49, v8
	v_div_scale_f32 v49, s[44:45], v8, v8, v91
	v_rcp_f32_e32 v90, v49
	s_mov_b64 s[44:45], 0
	v_fma_f32 v92, -v49, v90, 1.0
	v_fmac_f32_e32 v90, v92, v90
	v_div_scale_f32 v92, vcc, v91, v8, v91
	v_mul_f32_e32 v93, v92, v90
	v_fma_f32 v94, -v49, v93, v92
	v_fmac_f32_e32 v93, v94, v90
	v_fma_f32 v49, -v49, v93, v92
	v_div_fmas_f32 v49, v49, v90, v93
	v_div_fixup_f32 v8, v49, v8, v91
.LBB0_2007:
	s_andn2_b64 vcc, exec, s[44:45]
	v_mad_u64_u32 v[48:49], s[44:45], v48, s68, v[36:37]
	s_cbranch_vccnz .LBB0_2011
	s_and_saveexec_b64 s[44:45], s[8:9]
	v_lshl_add_u32 v8, v89, 2, v48
	ds_write_b32 v8, v4 offset:1584
	ds_write_b32 v8, v240 offset:50736
	s_or_b64 exec, exec, s[44:45]
	v_mov_b32_e32 v8, 0

.LBB0_2029:
	s_or_b64 exec, exec, s[44:45]
	v_max_f32_e32 v1, v89, v89
	v_max_f32_e32 v1, 0xf149f2ca, v1
	v_max3_f32 v1, v1, v4, v33
	v_max3_f32 v1, v1, v29, v90
	v_max3_f32 v1, v1, v25, v91
	v_max3_f32 v1, v1, v9, v92
	v_mov_b32_e32 v5, v37
	v_cmp_lt_f32_e32 vcc, s69, v89
	s_mov_b64 s[46:47], -1
	v_mov_b32_dpp v5, v1 row_ror:8 row_mask:0xf bank_mask:0xf
	v_max_f32_e32 v5, v5, v5
	v_max_f32_e32 v1, v1, v5
	v_mov_b32_e32 v5, v37
	s_nop 1
	v_mov_b32_dpp v5, v1 row_ror:4 row_mask:0xf bank_mask:0xf
	v_max_f32_e32 v5, v5, v5
	v_max_f32_e32 v1, v1, v5
	v_mov_b32_e32 v5, v37
	s_nop 1
	v_mov_b32_dpp v5, v1 row_ror:2 row_mask:0xf bank_mask:0xf
	v_max_f32_e32 v5, v5, v5
	v_max_f32_e32 v1, v1, v5
	v_mov_b32_e32 v5, v37
	s_nop 1
	v_mov_b32_dpp v5, v1 row_ror:1 row_mask:0xf bank_mask:0xf
	v_max_f32_e32 v5, v5, v5
	v_max_f32_e32 v93, v1, v5
	v_sub_f32_e32 v1, v89, v93
	v_mul_f32_e32 v1, 0x3fb8aa3b, v1
	v_sub_f32_e32 v5, v4, v93
	v_exp_f32_e32 v1, v1
	v_mul_f32_e32 v5, 0x3fb8aa3b, v5
	v_sub_f32_e32 v17, v33, v93
	v_exp_f32_e32 v5, v5
	v_mul_f32_e32 v17, 0x3fb8aa3b, v17
	v_exp_f32_e32 v17, v17
	v_cndmask_b32_e32 v1, 0, v1, vcc
	v_cmp_lt_f32_e32 vcc, s69, v4
	v_add_f32_e32 v13, 0, v1
	v_sub_f32_e32 v21, v90, v93
	v_cndmask_b32_e32 v5, 0, v5, vcc
	v_cmp_lt_f32_e32 vcc, s69, v33
	v_add_f32_e32 v4, v5, v13
	v_mul_f32_e32 v21, 0x3fb8aa3b, v21
	v_cndmask_b32_e32 v13, 0, v17, vcc
	v_sub_f32_e32 v17, v29, v93
	v_mul_f32_e32 v17, 0x3fb8aa3b, v17
	v_exp_f32_e32 v17, v17
	v_cmp_lt_f32_e32 vcc, s69, v29
	v_sub_f32_e32 v29, v25, v93
	v_exp_f32_e32 v21, v21
	v_mul_f32_e32 v29, 0x3fb8aa3b, v29
	v_sub_f32_e32 v33, v91, v93
	v_exp_f32_e32 v29, v29
	v_mul_f32_e32 v33, 0x3fb8aa3b, v33
	v_exp_f32_e32 v33, v33
	v_cndmask_b32_e32 v17, 0, v17, vcc
	v_cmp_lt_f32_e32 vcc, s69, v90
	v_sub_f32_e32 v36, v92, v93
	v_add_f32_e32 v4, v13, v4
	v_cndmask_b32_e32 v21, 0, v21, vcc
	v_cmp_lt_f32_e32 vcc, s69, v25
	v_mul_f32_e32 v36, 0x3fb8aa3b, v36
	v_add_f32_e32 v4, v17, v4
	v_cndmask_b32_e32 v25, 0, v29, vcc
	v_cmp_lt_f32_e32 vcc, s69, v91
	v_exp_f32_e32 v36, v36
	v_add_f32_e32 v4, v21, v4
	v_cndmask_b32_e32 v29, 0, v33, vcc
	v_sub_f32_e32 v33, v9, v93
	v_mul_f32_e32 v33, 0x3fb8aa3b, v33
	v_exp_f32_e32 v33, v33
	v_add_f32_e32 v4, v25, v4
	v_cmp_lt_f32_e32 vcc, s69, v9
	v_add_f32_e32 v4, v29, v4
	s_nop 0
	v_cndmask_b32_e32 v33, 0, v33, vcc
	v_cmp_lt_f32_e32 vcc, s69, v92
	v_add_f32_e32 v4, v33, v4
	s_nop 0
	v_cndmask_b32_e32 v36, 0, v36, vcc
	v_add_f32_e32 v4, v36, v4
	s_nop 1
	v_add_f32_dpp v4, v4, v4 row_ror:8 row_mask:0xf bank_mask:0xf bound_ctrl:1
	s_nop 1
	v_add_f32_dpp v4, v4, v4 row_ror:4 row_mask:0xf bank_mask:0xf bound_ctrl:1
	s_nop 1
	v_add_f32_dpp v4, v4, v4 row_ror:2 row_mask:0xf bank_mask:0xf bound_ctrl:1
	s_nop 1
	v_add_f32_dpp v91, v4, v4 row_ror:1 row_mask:0xf bank_mask:0xf bound_ctrl:1
	v_mov_b32_e32 v241, v91
	v_cmp_gt_f32_e32 vcc, s56, v91
	s_nop 1
	v_cndmask_b32_e64 v4, 0, 32, vcc
	v_ldexp_f32 v4, v91, v4
	v_log_f32_e32 v4, v4
	s_nop 0
	v_mul_f32_e32 v9, 0x3f317217, v4
	v_fma_f32 v9, v4, s57, -v9
	v_fmac_f32_e32 v9, 0x3377d1cf, v4
	v_fmac_f32_e32 v9, 0x3f317217, v4
	v_cmp_lt_f32_e64 s[44:45], |v4|, s58
	s_nop 1
	v_cndmask_b32_e64 v4, v4, v9, s[44:45]
	v_cndmask_b32_e32 v9, 0, v55, vcc
	v_sub_f32_e32 v4, v4, v9
	v_add_f32_e32 v89, v93, v4
	v_or_b32_e32 v4, 1, v0
	v_cndmask_b32_e64 v9, 0, 1, s[52:53]
	v_lshl_add_u32 v90, v4, v73, v87
	v_cmp_ne_u32_e64 s[44:45], 1, v9
	s_andn2_b64 vcc, exec, s[52:53]
	s_cbranch_vccnz .LBB0_2031
	v_lshlrev_b32_e32 v9, 2, v90
	v_add_u32_e32 v92, 48, v9
	ds_read_b32 v9, v9 offset:3632
	ds_read2st64_b32 v[92:93], v92 offset0:6 offset1:10
	s_waitcnt lgkmcnt(0)
	v_max3_f32 v94, v92, v93, v9
	v_sub_f32_e32 v92, v92, v94
	v_sub_f32_e32 v93, v93, v94
	v_mul_f32_e32 v92, 0x3fb8aa3b, v92
	v_mul_f32_e32 v93, 0x3fb8aa3b, v93
	v_exp_f32_e32 v92, v92
	v_exp_f32_e32 v93, v93
	v_sub_f32_e32 v9, v9, v94
	v_mul_f32_e32 v9, 0x3fb8aa3b, v9
	v_exp_f32_e32 v9, v9
	v_add_f32_e32 v92, v92, v93
	v_sub_f32_e32 v93, v89, v94
	v_mul_f32_e32 v93, 0x3fb8aa3b, v93
	v_exp_f32_e32 v93, v93
	v_add_f32_e32 v9, v9, v92
	v_mul_f32_e32 v9, v91, v9
	v_div_scale_f32 v91, s[46:47], v9, v9, v93
	v_rcp_f32_e32 v92, v91
	s_mov_b64 s[46:47], 0
	v_fma_f32 v94, -v91, v92, 1.0
	v_fmac_f32_e32 v92, v94, v92
	v_div_scale_f32 v94, vcc, v93, v9, v93
	v_mul_f32_e32 v95, v94, v92
	v_fma_f32 v96, -v91, v95, v94
	v_fmac_f32_e32 v95, v96, v92
	v_fma_f32 v91, -v91, v95, v94
	v_div_fmas_f32 v91, v91, v92, v95
	v_div_fixup_f32 v9, v91, v9, v93
.LBB0_2031:
	s_andn2_b64 vcc, exec, s[46:47]
	s_cbranch_vccnz .LBB0_2035
	s_and_saveexec_b64 s[46:47], s[8:9]
	v_lshl_add_u32 v9, v90, 2, v48
	ds_write_b32 v9, v89 offset:1584
	ds_write_b32 v9, v241 offset:50736
	s_or_b64 exec, exec, s[46:47]
	v_mov_b32_e32 v9, 0

.LBB0_2051:
	s_or_b64 exec, exec, s[46:47]
	v_max_f32_e32 v6, v90, v90
	v_max_f32_e32 v6, 0xf149f2ca, v6
	v_max3_f32 v6, v6, v89, v91
	v_max3_f32 v6, v6, v30, v92
	v_max3_f32 v6, v6, v34, v10
	v_max3_f32 v6, v6, v2, v93
	v_mov_b32_e32 v14, v37
	v_cmp_lt_f32_e32 vcc, s69, v90
	s_nop 0
	v_mov_b32_dpp v14, v6 row_ror:8 row_mask:0xf bank_mask:0xf
	v_max_f32_e32 v14, v14, v14
	v_max_f32_e32 v6, v6, v14
	v_mov_b32_e32 v14, v37
	s_nop 1
	v_mov_b32_dpp v14, v6 row_ror:4 row_mask:0xf bank_mask:0xf
	v_max_f32_e32 v14, v14, v14
	v_max_f32_e32 v6, v6, v14
	v_mov_b32_e32 v14, v37
	s_nop 1
	v_mov_b32_dpp v14, v6 row_ror:2 row_mask:0xf bank_mask:0xf
	v_max_f32_e32 v14, v14, v14
	v_max_f32_e32 v6, v6, v14
	v_mov_b32_e32 v14, v37
	s_nop 1
	v_mov_b32_dpp v14, v6 row_ror:1 row_mask:0xf bank_mask:0xf
	v_max_f32_e32 v14, v14, v14
	v_max_f32_e32 v6, v6, v14
	v_sub_f32_e32 v14, v90, v6
	v_mul_f32_e32 v14, 0x3fb8aa3b, v14
	v_sub_f32_e32 v18, v89, v6
	v_exp_f32_e32 v14, v14
	v_mul_f32_e32 v18, 0x3fb8aa3b, v18
	v_sub_f32_e32 v26, v91, v6
	v_exp_f32_e32 v18, v18
	v_mul_f32_e32 v26, 0x3fb8aa3b, v26
	v_exp_f32_e32 v26, v26
	v_cndmask_b32_e32 v14, 0, v14, vcc
	v_cmp_lt_f32_e32 vcc, s69, v89
	v_add_f32_e32 v22, 0, v14
	v_sub_f32_e32 v90, v92, v6
	v_cndmask_b32_e32 v18, 0, v18, vcc
	v_cmp_lt_f32_e32 vcc, s69, v91
	v_add_f32_e32 v89, v18, v22
	v_mul_f32_e32 v90, 0x3fb8aa3b, v90
	v_cndmask_b32_e32 v22, 0, v26, vcc
	v_sub_f32_e32 v26, v30, v6
	v_mul_f32_e32 v26, 0x3fb8aa3b, v26
	v_exp_f32_e32 v26, v26
	v_exp_f32_e32 v90, v90
	v_cmp_lt_f32_e32 vcc, s69, v30
	v_sub_f32_e32 v91, v10, v6
	v_mul_f32_e32 v91, 0x3fb8aa3b, v91
	v_cndmask_b32_e32 v26, 0, v26, vcc
	v_cmp_lt_f32_e32 vcc, s69, v92
	v_exp_f32_e32 v91, v91
	v_add_f32_e32 v89, v22, v89
	v_cndmask_b32_e32 v30, 0, v90, vcc
	v_sub_f32_e32 v90, v34, v6
	v_mul_f32_e32 v90, 0x3fb8aa3b, v90
	v_exp_f32_e32 v90, v90
	v_add_f32_e32 v89, v26, v89
	v_cmp_lt_f32_e32 vcc, s69, v34
	v_add_f32_e32 v89, v30, v89
	s_nop 0
	v_cndmask_b32_e32 v34, 0, v90, vcc
	v_cmp_lt_f32_e32 vcc, s69, v10
	v_add_f32_e32 v90, v34, v89
	s_nop 0
	v_cndmask_b32_e32 v89, 0, v91, vcc
	v_add_f32_e32 v10, v89, v90
	v_sub_f32_e32 v90, v2, v6
	v_mul_f32_e32 v90, 0x3fb8aa3b, v90
	v_sub_f32_e32 v91, v93, v6
	v_exp_f32_e32 v90, v90
	v_mul_f32_e32 v91, 0x3fb8aa3b, v91
	v_exp_f32_e32 v91, v91
	v_cmp_lt_f32_e32 vcc, s69, v2
	s_nop 1
	v_cndmask_b32_e32 v90, 0, v90, vcc
	v_cmp_lt_f32_e32 vcc, s69, v93
	v_add_f32_e32 v2, v90, v10
	s_nop 0
	v_cndmask_b32_e32 v91, 0, v91, vcc
	v_add_f32_e32 v2, v91, v2
	s_nop 1
	v_add_f32_dpp v2, v2, v2 row_ror:8 row_mask:0xf bank_mask:0xf bound_ctrl:1
	s_nop 1
	v_add_f32_dpp v2, v2, v2 row_ror:4 row_mask:0xf bank_mask:0xf bound_ctrl:1
	s_nop 1
	v_add_f32_dpp v2, v2, v2 row_ror:2 row_mask:0xf bank_mask:0xf bound_ctrl:1
	s_nop 1
	v_add_f32_dpp v93, v2, v2 row_ror:1 row_mask:0xf bank_mask:0xf bound_ctrl:1
	v_mov_b32_e32 v242, v93
	v_cmp_gt_f32_e32 vcc, s56, v93
	s_nop 1
	v_cndmask_b32_e64 v2, 0, 32, vcc
	v_ldexp_f32 v2, v93, v2
	v_log_f32_e32 v2, v2
	s_nop 0
	v_mul_f32_e32 v10, 0x3f317217, v2
	v_fma_f32 v10, v2, s57, -v10
	v_fmac_f32_e32 v10, 0x3377d1cf, v2
	v_fmac_f32_e32 v10, 0x3f317217, v2
	v_cmp_lt_f32_e64 s[46:47], |v2|, s58
	s_nop 1
	v_cndmask_b32_e64 v2, v2, v10, s[46:47]
	v_cndmask_b32_e32 v10, 0, v55, vcc
	v_sub_f32_e32 v2, v2, v10
	v_add_f32_e32 v6, v6, v2
	v_or_b32_e32 v2, 2, v0
	v_lshl_add_u32 v92, v2, v73, v87
	s_and_b64 vcc, exec, s[44:45]
	s_mov_b64 s[46:47], -1
	s_cbranch_vccnz .LBB0_2053
	v_lshlrev_b32_e32 v10, 2, v92
	v_add_u32_e32 v94, 48, v10
	ds_read_b32 v10, v10 offset:3632
	ds_read2st64_b32 v[94:95], v94 offset0:6 offset1:10
	s_waitcnt lgkmcnt(0)
	v_max3_f32 v96, v94, v95, v10
	v_sub_f32_e32 v94, v94, v96
	v_sub_f32_e32 v95, v95, v96
	v_mul_f32_e32 v94, 0x3fb8aa3b, v94
	v_mul_f32_e32 v95, 0x3fb8aa3b, v95
	v_exp_f32_e32 v94, v94
	v_exp_f32_e32 v95, v95
	v_sub_f32_e32 v10, v10, v96
	v_mul_f32_e32 v10, 0x3fb8aa3b, v10
	v_exp_f32_e32 v10, v10
	v_add_f32_e32 v94, v94, v95
	v_sub_f32_e32 v95, v6, v96
	v_mul_f32_e32 v95, 0x3fb8aa3b, v95
	v_exp_f32_e32 v95, v95
	v_add_f32_e32 v10, v10, v94
	v_mul_f32_e32 v10, v93, v10
	v_div_scale_f32 v93, s[46:47], v10, v10, v95
	v_rcp_f32_e32 v94, v93
	s_mov_b64 s[46:47], 0
	v_fma_f32 v96, -v93, v94, 1.0
	v_fmac_f32_e32 v94, v96, v94
	v_div_scale_f32 v96, vcc, v95, v10, v95
	v_mul_f32_e32 v97, v96, v94
	v_fma_f32 v98, -v93, v97, v96
	v_fmac_f32_e32 v97, v98, v94
	v_fma_f32 v93, -v93, v97, v96
	v_div_fmas_f32 v93, v93, v94, v97
	v_div_fixup_f32 v10, v93, v10, v95
.LBB0_2053:
	s_andn2_b64 vcc, exec, s[46:47]
	s_cbranch_vccnz .LBB0_2057
	s_and_saveexec_b64 s[46:47], s[8:9]
	v_lshl_add_u32 v10, v92, 2, v48
	ds_write_b32 v10, v6 offset:1584
	ds_write_b32 v10, v242 offset:50736
	s_or_b64 exec, exec, s[46:47]
	v_mov_b32_e32 v10, 0

.LBB0_2073:
	s_or_b64 exec, exec, s[26:27]
	v_max_f32_e32 v3, v92, v92
	v_max_f32_e32 v3, 0xf149f2ca, v3
	v_max3_f32 v3, v3, v6, v35
	v_max3_f32 v3, v3, v31, v80
	v_max3_f32 v3, v3, v27, v81
	v_max3_f32 v3, v3, v11, v82
	v_mov_b32_e32 v7, v37
	v_cmp_lt_f32_e32 vcc, s69, v92
	s_nop 0
	v_mov_b32_dpp v7, v3 row_ror:8 row_mask:0xf bank_mask:0xf
	v_max_f32_e32 v7, v7, v7
	v_max_f32_e32 v3, v3, v7
	v_mov_b32_e32 v7, v37
	s_nop 1
	v_mov_b32_dpp v7, v3 row_ror:4 row_mask:0xf bank_mask:0xf
	v_max_f32_e32 v7, v7, v7
	v_max_f32_e32 v3, v3, v7
	v_mov_b32_e32 v7, v37
	s_nop 1
	v_mov_b32_dpp v7, v3 row_ror:2 row_mask:0xf bank_mask:0xf
	v_max_f32_e32 v7, v7, v7
	v_max_f32_e32 v3, v3, v7
	v_mov_b32_e32 v7, v37
	s_nop 1
	v_mov_b32_dpp v7, v3 row_ror:1 row_mask:0xf bank_mask:0xf
	v_max_f32_e32 v7, v7, v7
	v_max_f32_e32 v83, v3, v7
	v_sub_f32_e32 v3, v92, v83
	v_mul_f32_e32 v3, 0x3fb8aa3b, v3
	v_sub_f32_e32 v7, v6, v83
	v_exp_f32_e32 v3, v3
	v_mul_f32_e32 v7, 0x3fb8aa3b, v7
	v_sub_f32_e32 v19, v35, v83
	v_exp_f32_e32 v7, v7
	v_mul_f32_e32 v19, 0x3fb8aa3b, v19
	v_exp_f32_e32 v19, v19
	v_cndmask_b32_e32 v3, 0, v3, vcc
	v_cmp_lt_f32_e32 vcc, s69, v6
	v_add_f32_e32 v15, 0, v3
	v_sub_f32_e32 v23, v80, v83
	v_cndmask_b32_e32 v7, 0, v7, vcc
	v_cmp_lt_f32_e32 vcc, s69, v35
	v_add_f32_e32 v6, v7, v15
	v_mul_f32_e32 v23, 0x3fb8aa3b, v23
	v_cndmask_b32_e32 v15, 0, v19, vcc
	v_sub_f32_e32 v19, v31, v83
	v_mul_f32_e32 v19, 0x3fb8aa3b, v19
	v_exp_f32_e32 v19, v19
	v_cmp_lt_f32_e32 vcc, s69, v31
	v_sub_f32_e32 v31, v27, v83
	v_exp_f32_e32 v23, v23
	v_mul_f32_e32 v31, 0x3fb8aa3b, v31
	v_sub_f32_e32 v35, v81, v83
	v_exp_f32_e32 v31, v31
	v_mul_f32_e32 v35, 0x3fb8aa3b, v35
	v_exp_f32_e32 v35, v35
	v_cndmask_b32_e32 v19, 0, v19, vcc
	v_cmp_lt_f32_e32 vcc, s69, v80
	v_sub_f32_e32 v49, v82, v83
	v_add_f32_e32 v6, v15, v6
	v_cndmask_b32_e32 v23, 0, v23, vcc
	v_cmp_lt_f32_e32 vcc, s69, v27
	v_mul_f32_e32 v49, 0x3fb8aa3b, v49
	v_add_f32_e32 v6, v19, v6
	v_cndmask_b32_e32 v27, 0, v31, vcc
	v_cmp_lt_f32_e32 vcc, s69, v81
	v_exp_f32_e32 v49, v49
	v_add_f32_e32 v6, v23, v6
	v_cndmask_b32_e32 v31, 0, v35, vcc
	v_sub_f32_e32 v35, v11, v83
	v_mul_f32_e32 v35, 0x3fb8aa3b, v35
	v_exp_f32_e32 v35, v35
	v_add_f32_e32 v6, v27, v6
	v_cmp_lt_f32_e32 vcc, s69, v11
	v_add_f32_e32 v6, v31, v6
	s_nop 0
	v_cndmask_b32_e32 v35, 0, v35, vcc
	v_cmp_lt_f32_e32 vcc, s69, v82
	v_add_f32_e32 v6, v35, v6
	s_nop 0
	v_cndmask_b32_e32 v49, 0, v49, vcc
	v_add_f32_e32 v6, v49, v6
	s_nop 1
	v_add_f32_dpp v6, v6, v6 row_ror:8 row_mask:0xf bank_mask:0xf bound_ctrl:1
	s_nop 1
	v_add_f32_dpp v6, v6, v6 row_ror:4 row_mask:0xf bank_mask:0xf bound_ctrl:1
	s_nop 1
	v_add_f32_dpp v6, v6, v6 row_ror:2 row_mask:0xf bank_mask:0xf bound_ctrl:1
	s_nop 1
	v_add_f32_dpp v82, v6, v6 row_ror:1 row_mask:0xf bank_mask:0xf bound_ctrl:1
	v_mov_b32_e32 v243, v82
	v_cmp_gt_f32_e32 vcc, s56, v82
	s_nop 1
	v_cndmask_b32_e64 v6, 0, 32, vcc
	v_ldexp_f32 v6, v82, v6
	v_log_f32_e32 v6, v6
	s_nop 0
	v_mul_f32_e32 v11, 0x3f317217, v6
	v_fma_f32 v11, v6, s57, -v11
	v_fmac_f32_e32 v11, 0x3377d1cf, v6
	v_fmac_f32_e32 v11, 0x3f317217, v6
	v_cmp_lt_f32_e64 s[26:27], |v6|, s58
	s_nop 1
	v_cndmask_b32_e64 v6, v6, v11, s[26:27]
	v_cndmask_b32_e32 v11, 0, v55, vcc
	v_sub_f32_e32 v6, v6, v11
	v_add_f32_e32 v80, v83, v6
	v_or_b32_e32 v6, 3, v0
	v_lshl_add_u32 v81, v6, v73, v87
	s_and_b64 vcc, exec, s[44:45]
	s_mov_b64 s[26:27], -1
	s_cbranch_vccnz .LBB0_2080
	v_lshlrev_b32_e32 v11, 2, v81
	v_add_u32_e32 v83, 48, v11
	ds_read_b32 v11, v11 offset:3632
	ds_read2st64_b32 v[84:85], v83 offset0:6 offset1:10
	s_waitcnt lgkmcnt(0)
	v_max3_f32 v83, v84, v85, v11
	v_sub_f32_e32 v84, v84, v83
	v_sub_f32_e32 v85, v85, v83
	v_mul_f32_e32 v84, 0x3fb8aa3b, v84
	v_mul_f32_e32 v85, 0x3fb8aa3b, v85
	v_sub_f32_e32 v11, v11, v83
	v_exp_f32_e32 v84, v84
	v_exp_f32_e32 v85, v85
	v_mul_f32_e32 v11, 0x3fb8aa3b, v11
	v_exp_f32_e32 v11, v11
	v_sub_f32_e32 v83, v80, v83
	v_mul_f32_e32 v83, 0x3fb8aa3b, v83
	v_exp_f32_e32 v83, v83
	v_add_f32_e32 v84, v84, v85
	v_add_f32_e32 v11, v11, v84
	v_mul_f32_e32 v11, v82, v11
	v_div_scale_f32 v82, s[26:27], v11, v11, v83
	v_rcp_f32_e32 v84, v82
	s_nop 0
	v_fma_f32 v85, -v82, v84, 1.0
	v_fmac_f32_e32 v84, v85, v84
	v_div_scale_f32 v85, vcc, v83, v11, v83
	v_mul_f32_e32 v86, v85, v84
	v_fma_f32 v87, -v82, v86, v85
	v_fmac_f32_e32 v86, v87, v84
	v_fma_f32 v82, -v82, v86, v85
	v_div_fmas_f32 v82, v82, v84, v86
	v_div_fixup_f32 v11, v82, v11, v83
	s_cbranch_execz .LBB0_2081
.LBB0_2075:
	s_branch .LBB0_2084
.LBB0_2076:
	s_or_b64 exec, exec, s[46:47]
	s_and_saveexec_b64 s[46:47], s[42:43]
	s_cbranch_execz .LBB0_2049

.LBB0_2081:
	s_and_saveexec_b64 s[26:27], s[8:9]
	v_lshl_add_u32 v11, v81, 2, v48
	ds_write_b32 v11, v80 offset:1584
	ds_write_b32 v11, v243 offset:50736
	s_or_b64 exec, exec, s[26:27]
	v_mov_b32_e32 v11, 0
.LBB0_2084:
	s_mov_b64 s[52:53], -1
	v_bfe_u32 v48, v12, 16, 1
	v_add3_u32 v12, v12, v48, s70
	ds_write_b16_d16_hi v54, v12 offset:4688
	v_bfe_u32 v12, v16, 16, 1
	v_add3_u32 v12, v16, v12, s70
	ds_write_b16_d16_hi v54, v12 offset:4720
	v_bfe_u32 v12, v20, 16, 1
	v_add3_u32 v12, v20, v12, s70
	ds_write_b16_d16_hi v54, v12 offset:4752
	v_bfe_u32 v12, v24, 16, 1
	v_add3_u32 v12, v24, v12, s70
	ds_write_b16_d16_hi v54, v12 offset:4784
	v_bfe_u32 v12, v28, 16, 1
	v_add3_u32 v12, v28, v12, s70
	ds_write_b16_d16_hi v54, v12 offset:4816
	v_bfe_u32 v12, v32, 16, 1
	v_add3_u32 v12, v32, v12, s70
	ds_write_b16_d16_hi v54, v12 offset:4848
	v_bfe_u32 v12, v77, 16, 1
	v_add3_u32 v12, v77, v12, s70
	ds_write_b16_d16_hi v54, v12 offset:4880
	v_bfe_u32 v12, v78, 16, 1
	v_add3_u32 v12, v78, v12, s70
	ds_write_b16_d16_hi v54, v12 offset:4912
	v_bfe_u32 v12, v79, 16, 1
	v_add3_u32 v12, v79, v12, s70
	ds_write_b16 v54, v37 offset:4656
	ds_write_b16_d16_hi v54, v12 offset:4944
	ds_write_b16 v54, v37 offset:4992
	v_bfe_u32 v12, v1, 16, 1
	v_add3_u32 v1, v1, v12, s70
	ds_write_b16_d16_hi v54, v1 offset:5024
	v_bfe_u32 v1, v5, 16, 1
	v_add3_u32 v1, v5, v1, s70
	ds_write_b16_d16_hi v54, v1 offset:5056
	v_bfe_u32 v1, v13, 16, 1
	v_add3_u32 v1, v13, v1, s70
	ds_write_b16_d16_hi v54, v1 offset:5088
	v_bfe_u32 v1, v17, 16, 1
	v_add3_u32 v1, v17, v1, s70
	ds_write_b16_d16_hi v54, v1 offset:5120
	v_bfe_u32 v1, v21, 16, 1
	v_add3_u32 v1, v21, v1, s70
	ds_write_b16_d16_hi v54, v1 offset:5152
	v_bfe_u32 v1, v25, 16, 1
	v_add3_u32 v1, v25, v1, s70
	ds_write_b16_d16_hi v54, v1 offset:5184
	v_bfe_u32 v1, v29, 16, 1
	v_add3_u32 v1, v29, v1, s70
	ds_write_b16_d16_hi v54, v1 offset:5216
	v_bfe_u32 v1, v33, 16, 1
	v_add3_u32 v1, v33, v1, s70
	ds_write_b16_d16_hi v54, v1 offset:5248
	v_bfe_u32 v1, v36, 16, 1
	v_add3_u32 v1, v36, v1, s70
	ds_write_b16_d16_hi v54, v1 offset:5280
	ds_write_b16 v54, v37 offset:5328
	v_bfe_u32 v1, v14, 16, 1
	v_add3_u32 v1, v14, v1, s70
	ds_write_b16_d16_hi v54, v1 offset:5360
	v_bfe_u32 v1, v18, 16, 1
	v_add3_u32 v1, v18, v1, s70
	ds_write_b16_d16_hi v54, v1 offset:5392
	v_bfe_u32 v1, v22, 16, 1
	v_add3_u32 v1, v22, v1, s70
	ds_write_b16_d16_hi v54, v1 offset:5424
	v_bfe_u32 v1, v26, 16, 1
	v_add3_u32 v1, v26, v1, s70
	ds_write_b16_d16_hi v54, v1 offset:5456
	v_bfe_u32 v1, v30, 16, 1
	v_add3_u32 v1, v30, v1, s70
	ds_write_b16_d16_hi v54, v1 offset:5488
	v_bfe_u32 v1, v34, 16, 1
	v_add3_u32 v1, v34, v1, s70
	ds_write_b16_d16_hi v54, v1 offset:5520
	v_bfe_u32 v1, v89, 16, 1
	v_add3_u32 v1, v89, v1, s70
	ds_write_b16_d16_hi v54, v1 offset:5552
	v_bfe_u32 v1, v90, 16, 1
	v_add3_u32 v1, v90, v1, s70
	ds_write_b16_d16_hi v54, v1 offset:5584
	v_bfe_u32 v1, v91, 16, 1
	v_add3_u32 v1, v91, v1, s70
	ds_write_b16_d16_hi v54, v1 offset:5616
	ds_write_b16 v54, v37 offset:5664
	v_bfe_u32 v1, v3, 16, 1
	v_add3_u32 v1, v3, v1, s70
	ds_write_b16_d16_hi v54, v1 offset:5696
	v_bfe_u32 v1, v7, 16, 1
	v_add3_u32 v1, v7, v1, s70
	ds_write_b16_d16_hi v54, v1 offset:5728
	v_bfe_u32 v1, v15, 16, 1
	v_add3_u32 v1, v15, v1, s70
	ds_write_b16_d16_hi v54, v1 offset:5760
	v_bfe_u32 v1, v19, 16, 1
	v_add3_u32 v1, v19, v1, s70
	ds_write_b16_d16_hi v54, v1 offset:5792
	v_bfe_u32 v1, v23, 16, 1
	v_add3_u32 v1, v23, v1, s70
	ds_write_b16_d16_hi v54, v1 offset:5824
	v_bfe_u32 v1, v27, 16, 1
	v_add3_u32 v1, v27, v1, s70
	ds_write_b16_d16_hi v54, v1 offset:5856
	v_bfe_u32 v1, v31, 16, 1
	v_add3_u32 v1, v31, v1, s70
	ds_write_b16_d16_hi v54, v1 offset:5888
	v_bfe_u32 v1, v35, 16, 1
	v_add3_u32 v1, v35, v1, s70
	ds_write_b16_d16_hi v54, v1 offset:5920
	v_bfe_u32 v1, v49, 16, 1
	v_add3_u32 v1, v49, v1, s70
	ds_write_b16_d16_hi v54, v1 offset:5952
	ds_read_b128 v[100:103], v56 offset:4656
	ds_read_b128 v[104:107], v56 offset:4720
	ds_read_b128 v[108:111], v56 offset:4784
	ds_read_b128 v[112:115], v56 offset:4848
	ds_read_b128 v[116:119], v56 offset:4912
	s_waitcnt vmcnt(0) lgkmcnt(0)
	v_mfma_f32_16x16x32_bf16 v[12:15], v[100:103], v[120:123], 0
	v_mfma_f32_16x16x32_bf16 v[16:19], v[100:103], v[124:127], 0
	v_mfma_f32_16x16x32_bf16 v[28:31], v[100:103], v[128:131], 0
	v_mfma_f32_16x16x32_bf16 v[20:23], v[100:103], v[132:135], 0
	v_mfma_f32_16x16x32_bf16 v[12:15], v[104:107], v[136:139], v[12:15]
	v_mfma_f32_16x16x32_bf16 v[16:19], v[104:107], v[140:143], v[16:19]
	v_mfma_f32_16x16x32_bf16 v[28:31], v[104:107], v[144:147], v[28:31]
	v_mfma_f32_16x16x32_bf16 v[20:23], v[104:107], v[148:151], v[20:23]
	v_mfma_f32_16x16x32_bf16 v[12:15], v[108:111], v[152:155], v[12:15]
	v_mfma_f32_16x16x32_bf16 v[16:19], v[108:111], v[156:159], v[16:19]
	v_mfma_f32_16x16x32_bf16 v[28:31], v[108:111], v[160:163], v[28:31]
	v_mfma_f32_16x16x32_bf16 v[20:23], v[108:111], v[164:167], v[20:23]
	v_mfma_f32_16x16x32_bf16 v[12:15], v[112:115], v[168:171], v[12:15]
	v_mfma_f32_16x16x32_bf16 v[16:19], v[112:115], v[172:175], v[16:19]
	v_mfma_f32_16x16x32_bf16 v[28:31], v[112:115], v[180:183], v[28:31]
	v_mfma_f32_16x16x32_bf16 v[20:23], v[112:115], v[184:187], v[20:23]
	v_mfma_f32_16x16x32_bf16 v[12:15], v[116:119], v[188:191], v[12:15]
	v_mfma_f32_16x16x32_bf16 v[16:19], v[116:119], v[192:195], v[16:19]
	v_mfma_f32_16x16x32_bf16 v[28:31], v[116:119], v[196:199], v[28:31]
	v_mfma_f32_16x16x32_bf16 v[20:23], v[116:119], v[200:203], v[20:23]
	s_nop 7
	s_nop 1
	v_lshlrev_b32_e32 v1, 6, v74
	v_lshlrev_b32_e32 v36, 1, v1
	v_subrev_u32_e32 v232, s48, v42
	v_add_u32_e32 v232, v232, v36
	v_mov_b32_e32 v228, s48
	v_mov_b32_e32 v229, s49
	v_mov_b32_e32 v230, 0xee000000
	v_mov_b32_e32 v231, -1
	v_lshl_add_u64 v[228:229], v[228:229], 0, v[230:231]
	v_lshlrev_b32_e32 v220, v73, v0
	v_add_u32_e32 v220, v220, v46
	v_lshlrev_b32_e32 v220, 11, v220
	v_add_u32_e32 v220, v220, v232
	v_lshlrev_b32_e32 v220, 1, v220
	v_mov_b32_e32 v221, 0
	v_lshl_add_u64 v[220:221], v[220:221], 0, v[228:229]
	v_lshlrev_b32_e32 v222, v73, v4
	v_add_u32_e32 v222, v222, v46
	v_lshlrev_b32_e32 v222, 11, v222
	v_add_u32_e32 v222, v222, v232
	v_lshlrev_b32_e32 v222, 1, v222
	v_mov_b32_e32 v223, 0
	v_lshl_add_u64 v[222:223], v[222:223], 0, v[228:229]
	v_lshlrev_b32_e32 v224, v73, v2
	v_add_u32_e32 v224, v224, v46
	v_lshlrev_b32_e32 v224, 11, v224
	v_add_u32_e32 v224, v224, v232
	v_lshlrev_b32_e32 v224, 1, v224
	v_mov_b32_e32 v225, 0
	v_lshl_add_u64 v[224:225], v[224:225], 0, v[228:229]
	v_lshlrev_b32_e32 v226, v73, v6
	v_add_u32_e32 v226, v226, v46
	v_lshlrev_b32_e32 v226, 11, v226
	v_add_u32_e32 v226, v226, v232
	v_lshlrev_b32_e32 v226, 1, v226
	v_mov_b32_e32 v227, 0
	v_lshl_add_u64 v[226:227], v[226:227], 0, v[228:229]
	global_store_dword v[220:221], v12, off
	global_store_dword v[222:223], v13, off
	global_store_dword v[224:225], v14, off
	global_store_dword v[226:227], v15, off
	global_store_dword v[220:221], v16, off offset:64
	global_store_dword v[222:223], v17, off offset:64
	global_store_dword v[224:225], v18, off offset:64
	global_store_dword v[226:227], v19, off offset:64
	global_store_dword v[220:221], v28, off offset:128
	global_store_dword v[222:223], v29, off offset:128
	global_store_dword v[224:225], v30, off offset:128
	global_store_dword v[226:227], v31, off offset:128
	global_store_dword v[220:221], v20, off offset:192
	global_store_dword v[222:223], v21, off offset:192
	global_store_dword v[224:225], v22, off offset:192
	global_store_dword v[226:227], v23, off offset:192
	s_branch .LBB0_1986
